# P2 V-tile epilogue: V^T fragment scatter staged through a per-wave LDS slot (16 KiB static LDS), one 16-byte store per lane per 1 KiB block instead of 128 two-byte stores
# speedup vs baseline: 1.0773x; 1.0046x over previous
.LBB0_374:
	s_add_u32 s42, s16, 0xfffc0080
	s_addc_u32 s43, s17, -1
	s_add_i32 s75, 0, 0x10000
	s_cmp_eq_u32 vcc_hi, 12
	s_cselect_b32 s45, s1, s43
	s_cselect_b32 s44, s0, s42
	s_cselect_b32 s43, s41, vcc_lo
	s_cselect_b32 s42, s40, s74
	s_add_i32 s81, 0, 0x14000
	v_add_u32_e32 v150, s75, v156
	v_add_u32_e32 v154, s81, v156
	ds_read_b128 v[138:141], v150
	ds_read_b128 v[142:145], v150 offset:1024
	ds_read_b128 v[146:149], v150 offset:2048
	ds_read_b128 v[150:153], v150 offset:3072
	ds_read_b128 v[158:161], v154
	ds_read_b128 v[162:165], v154 offset:1024
	ds_read_b128 v[166:169], v154 offset:2048
	ds_read_b128 v[170:173], v154 offset:3072
	v_lshl_add_u64 v[154:155], s[16:17], 0, v[134:135]
	s_add_i32 m0, s33, 0xc000
	ds_read_b128 v[174:177], v157
	ds_read_b128 v[178:181], v157 offset:1024
	ds_read_b128 v[182:185], v157 offset:2048
	ds_read_b128 v[186:189], v157 offset:3072
	ds_read_b128 v[190:193], v157 offset:4096
	ds_read_b128 v[202:205], v157 offset:5120
	ds_read_b128 v[206:209], v157 offset:6144
	ds_read_b128 v[210:213], v157 offset:7168
	global_load_lds_dwordx4 v[154:155], off
	v_lshl_add_u64 v[154:155], s[16:17], 0, v[136:137]
	s_add_i32 m0, s33, 0xe000
	s_nop 0
	global_load_lds_dwordx4 v[154:155], off
	s_waitcnt vmcnt(8)
	s_waitcnt lgkmcnt(0)
	s_barrier
	s_setprio 1
	s_waitcnt lgkmcnt(0)
	v_mfma_f32_16x16x32_bf16 v[126:129], v[138:141], v[174:177], v[126:129]
	v_mfma_f32_16x16x32_bf16 v[122:125], v[146:149], v[174:177], v[122:125]
	v_mfma_f32_16x16x32_bf16 v[114:117], v[138:141], v[182:185], v[114:117]
	v_mfma_f32_16x16x32_bf16 v[106:109], v[146:149], v[182:185], v[106:109]
	v_mfma_f32_16x16x32_bf16 v[98:101], v[138:141], v[190:193], v[98:101]
	v_mfma_f32_16x16x32_bf16 v[90:93], v[146:149], v[190:193], v[90:93]
	v_mfma_f32_16x16x32_bf16 v[82:85], v[138:141], v[206:209], v[82:85]
	v_mfma_f32_16x16x32_bf16 v[74:77], v[146:149], v[206:209], v[74:77]
	v_mfma_f32_16x16x32_bf16 v[126:129], v[142:145], v[178:181], v[126:129]
	v_mfma_f32_16x16x32_bf16 v[122:125], v[150:153], v[178:181], v[122:125]
	v_mfma_f32_16x16x32_bf16 v[114:117], v[142:145], v[186:189], v[114:117]
	v_mfma_f32_16x16x32_bf16 v[106:109], v[150:153], v[186:189], v[106:109]
	v_mfma_f32_16x16x32_bf16 v[98:101], v[142:145], v[202:205], v[98:101]
	v_mfma_f32_16x16x32_bf16 v[90:93], v[150:153], v[202:205], v[90:93]
	v_mfma_f32_16x16x32_bf16 v[82:85], v[142:145], v[210:213], v[82:85]
	v_mfma_f32_16x16x32_bf16 v[74:77], v[150:153], v[210:213], v[74:77]
	s_setprio 0
	s_setprio 1
	v_mfma_f32_16x16x32_bf16 v[118:121], v[158:161], v[174:177], v[118:121]
	v_mfma_f32_16x16x32_bf16 v[110:113], v[166:169], v[174:177], v[110:113]
	v_mfma_f32_16x16x32_bf16 v[102:105], v[158:161], v[182:185], v[102:105]
	v_mfma_f32_16x16x32_bf16 v[94:97], v[166:169], v[182:185], v[94:97]
	v_mfma_f32_16x16x32_bf16 v[86:89], v[158:161], v[190:193], v[86:89]
	v_mfma_f32_16x16x32_bf16 v[78:81], v[166:169], v[190:193], v[78:81]
	v_mfma_f32_16x16x32_bf16 v[70:73], v[158:161], v[206:209], v[70:73]
	v_mfma_f32_16x16x32_bf16 v[66:69], v[166:169], v[206:209], v[66:69]
	v_mfma_f32_16x16x32_bf16 v[118:121], v[162:165], v[178:181], v[118:121]
	v_mfma_f32_16x16x32_bf16 v[110:113], v[170:173], v[178:181], v[110:113]
	v_mfma_f32_16x16x32_bf16 v[102:105], v[162:165], v[186:189], v[102:105]
	v_mfma_f32_16x16x32_bf16 v[94:97], v[170:173], v[186:189], v[94:97]
	v_mfma_f32_16x16x32_bf16 v[86:89], v[162:165], v[202:205], v[86:89]
	v_mfma_f32_16x16x32_bf16 v[78:81], v[170:173], v[202:205], v[78:81]
	v_mfma_f32_16x16x32_bf16 v[70:73], v[162:165], v[210:213], v[70:73]
	v_mfma_f32_16x16x32_bf16 v[66:69], v[170:173], v[210:213], v[66:69]
	s_setprio 0
	s_barrier
	s_add_i32 s75, s75, s15
	v_lshl_add_u64 v[154:155], s[42:43], 0, v[130:131]
	s_mov_b32 m0, s75
	ds_read_b128 v[174:177], v157 offset:16384
	ds_read_b128 v[178:181], v157 offset:17408
	ds_read_b128 v[182:185], v157 offset:18432
	ds_read_b128 v[186:189], v157 offset:19456
	ds_read_b128 v[190:193], v157 offset:20480
	ds_read_b128 v[202:205], v157 offset:21504
	ds_read_b128 v[206:209], v157 offset:22528
	ds_read_b128 v[210:213], v157 offset:23552
	global_load_lds_dwordx4 v[154:155], off
	s_add_i32 m0, s75, 0x2000
	s_add_u32 s76, s42, 0x40000
	v_lshl_add_u64 v[194:195], s[42:43], 0, v[132:133]
	s_addc_u32 s77, s43, 0
	s_add_i32 s75, s81, s15
	global_load_lds_dwordx4 v[194:195], off
	v_lshl_add_u64 v[198:199], s[76:77], 0, v[130:131]
	s_mov_b32 m0, s75
	v_lshl_add_u64 v[200:201], s[44:45], 0, v[132:133]
	global_load_lds_dwordx4 v[198:199], off
	v_lshl_add_u64 v[198:199], s[76:77], 0, v[132:133]
	s_add_i32 m0, s75, 0x2000
	s_nop 0
	global_load_lds_dwordx4 v[198:199], off
	v_lshl_add_u64 v[198:199], s[44:45], 0, v[130:131]
	s_mov_b32 m0, s33
	s_nop 0
	global_load_lds_dwordx4 v[198:199], off
	s_mov_b32 m0, s68
	s_nop 0
	global_load_lds_dwordx4 v[200:201], off
	s_waitcnt vmcnt(8)
	s_waitcnt lgkmcnt(0)
	s_barrier
	s_setprio 1
	s_waitcnt lgkmcnt(0)
	v_mfma_f32_16x16x32_bf16 v[62:65], v[138:141], v[174:177], v[62:65]
	v_mfma_f32_16x16x32_bf16 v[58:61], v[146:149], v[174:177], v[58:61]
	v_mfma_f32_16x16x32_bf16 v[50:53], v[138:141], v[182:185], v[50:53]
	v_mfma_f32_16x16x32_bf16 v[42:45], v[146:149], v[182:185], v[42:45]
	v_mfma_f32_16x16x32_bf16 v[34:37], v[138:141], v[190:193], v[34:37]
	v_mfma_f32_16x16x32_bf16 v[26:29], v[146:149], v[190:193], v[26:29]
	v_mfma_f32_16x16x32_bf16 v[18:21], v[138:141], v[206:209], v[18:21]
	v_mfma_f32_16x16x32_bf16 v[10:13], v[146:149], v[206:209], v[10:13]
	v_mfma_f32_16x16x32_bf16 v[62:65], v[142:145], v[178:181], v[62:65]
	v_mfma_f32_16x16x32_bf16 v[58:61], v[150:153], v[178:181], v[58:61]
	v_mfma_f32_16x16x32_bf16 v[50:53], v[142:145], v[186:189], v[50:53]
	v_mfma_f32_16x16x32_bf16 v[42:45], v[150:153], v[186:189], v[42:45]
	v_mfma_f32_16x16x32_bf16 v[34:37], v[142:145], v[202:205], v[34:37]
	v_mfma_f32_16x16x32_bf16 v[26:29], v[150:153], v[202:205], v[26:29]
	v_mfma_f32_16x16x32_bf16 v[18:21], v[142:145], v[210:213], v[18:21]
	v_mfma_f32_16x16x32_bf16 v[10:13], v[150:153], v[210:213], v[10:13]
	s_setprio 0
	s_setprio 1
	v_mfma_f32_16x16x32_bf16 v[54:57], v[158:161], v[174:177], v[54:57]
	v_mfma_f32_16x16x32_bf16 v[46:49], v[166:169], v[174:177], v[46:49]
	v_mfma_f32_16x16x32_bf16 v[38:41], v[158:161], v[182:185], v[38:41]
	v_mfma_f32_16x16x32_bf16 v[30:33], v[166:169], v[182:185], v[30:33]
	v_mfma_f32_16x16x32_bf16 v[22:25], v[158:161], v[190:193], v[22:25]
	v_mfma_f32_16x16x32_bf16 v[14:17], v[166:169], v[190:193], v[14:17]
	v_mfma_f32_16x16x32_bf16 v[6:9], v[158:161], v[206:209], v[6:9]
	v_mfma_f32_16x16x32_bf16 v[2:5], v[166:169], v[206:209], v[2:5]
	v_mfma_f32_16x16x32_bf16 v[54:57], v[162:165], v[178:181], v[54:57]
	v_mfma_f32_16x16x32_bf16 v[46:49], v[170:173], v[178:181], v[46:49]
	v_mfma_f32_16x16x32_bf16 v[38:41], v[162:165], v[186:189], v[38:41]
	v_mfma_f32_16x16x32_bf16 v[30:33], v[170:173], v[186:189], v[30:33]
	v_mfma_f32_16x16x32_bf16 v[22:25], v[162:165], v[202:205], v[22:25]
	v_mfma_f32_16x16x32_bf16 v[14:17], v[170:173], v[202:205], v[14:17]
	v_mfma_f32_16x16x32_bf16 v[6:9], v[162:165], v[210:213], v[6:9]
	v_mfma_f32_16x16x32_bf16 v[2:5], v[170:173], v[210:213], v[2:5]
	s_setprio 0
	s_barrier
	s_add_i32 s75, 0, 0x18000
	s_add_i32 s76, 0, 0x1c000
	v_add_u32_e32 v150, s75, v156
	v_add_u32_e32 v170, s76, v156
	ds_read_b128 v[138:141], v150
	ds_read_b128 v[142:145], v150 offset:1024
	ds_read_b128 v[146:149], v150 offset:2048
	ds_read_b128 v[150:153], v150 offset:3072
	ds_read_b128 v[158:161], v170
	ds_read_b128 v[162:165], v170 offset:1024
	ds_read_b128 v[166:169], v170 offset:2048
	ds_read_b128 v[170:173], v170 offset:3072
	s_add_u32 s44, s44, 0x40000
	s_addc_u32 s45, s45, 0
	s_mov_b32 m0, s69
	v_lshl_add_u64 v[214:215], s[44:45], 0, v[130:131]
	ds_read_b128 v[174:177], v157 offset:32768
	ds_read_b128 v[178:181], v157 offset:33792
	ds_read_b128 v[182:185], v157 offset:34816
	ds_read_b128 v[186:189], v157 offset:35840
	ds_read_b128 v[190:193], v157 offset:36864
	ds_read_b128 v[202:205], v157 offset:37888
	ds_read_b128 v[206:209], v157 offset:38912
	ds_read_b128 v[210:213], v157 offset:39936
	global_load_lds_dwordx4 v[214:215], off
	v_lshl_add_u64 v[214:215], s[44:45], 0, v[132:133]
	s_mov_b32 m0, s70
	s_nop 0
	global_load_lds_dwordx4 v[214:215], off
	s_waitcnt vmcnt(8)
	s_waitcnt lgkmcnt(0)
	s_barrier
	s_setprio 1
	s_waitcnt lgkmcnt(0)
	v_mfma_f32_16x16x32_bf16 v[126:129], v[138:141], v[174:177], v[126:129]
	v_mfma_f32_16x16x32_bf16 v[122:125], v[146:149], v[174:177], v[122:125]
	v_mfma_f32_16x16x32_bf16 v[114:117], v[138:141], v[182:185], v[114:117]
	v_mfma_f32_16x16x32_bf16 v[106:109], v[146:149], v[182:185], v[106:109]
	v_mfma_f32_16x16x32_bf16 v[98:101], v[138:141], v[190:193], v[98:101]
	v_mfma_f32_16x16x32_bf16 v[90:93], v[146:149], v[190:193], v[90:93]
	v_mfma_f32_16x16x32_bf16 v[82:85], v[138:141], v[206:209], v[82:85]
	v_mfma_f32_16x16x32_bf16 v[74:77], v[146:149], v[206:209], v[74:77]
	v_mfma_f32_16x16x32_bf16 v[126:129], v[142:145], v[178:181], v[126:129]
	v_mfma_f32_16x16x32_bf16 v[122:125], v[150:153], v[178:181], v[122:125]
	v_mfma_f32_16x16x32_bf16 v[114:117], v[142:145], v[186:189], v[114:117]
	v_mfma_f32_16x16x32_bf16 v[106:109], v[150:153], v[186:189], v[106:109]
	v_mfma_f32_16x16x32_bf16 v[98:101], v[142:145], v[202:205], v[98:101]
	v_mfma_f32_16x16x32_bf16 v[90:93], v[150:153], v[202:205], v[90:93]
	v_mfma_f32_16x16x32_bf16 v[82:85], v[142:145], v[210:213], v[82:85]
	v_mfma_f32_16x16x32_bf16 v[74:77], v[150:153], v[210:213], v[74:77]
	s_setprio 0
	s_setprio 1
	v_mfma_f32_16x16x32_bf16 v[118:121], v[158:161], v[174:177], v[118:121]
	v_mfma_f32_16x16x32_bf16 v[110:113], v[166:169], v[174:177], v[110:113]
	v_mfma_f32_16x16x32_bf16 v[102:105], v[158:161], v[182:185], v[102:105]
	v_mfma_f32_16x16x32_bf16 v[94:97], v[166:169], v[182:185], v[94:97]
	v_mfma_f32_16x16x32_bf16 v[86:89], v[158:161], v[190:193], v[86:89]
	v_mfma_f32_16x16x32_bf16 v[78:81], v[166:169], v[190:193], v[78:81]
	v_mfma_f32_16x16x32_bf16 v[70:73], v[158:161], v[206:209], v[70:73]
	v_mfma_f32_16x16x32_bf16 v[66:69], v[166:169], v[206:209], v[66:69]
	v_mfma_f32_16x16x32_bf16 v[118:121], v[162:165], v[178:181], v[118:121]
	v_mfma_f32_16x16x32_bf16 v[110:113], v[170:173], v[178:181], v[110:113]
	v_mfma_f32_16x16x32_bf16 v[102:105], v[162:165], v[186:189], v[102:105]
	v_mfma_f32_16x16x32_bf16 v[94:97], v[170:173], v[186:189], v[94:97]
	v_mfma_f32_16x16x32_bf16 v[86:89], v[162:165], v[202:205], v[86:89]
	v_mfma_f32_16x16x32_bf16 v[78:81], v[170:173], v[202:205], v[78:81]
	v_mfma_f32_16x16x32_bf16 v[70:73], v[162:165], v[210:213], v[70:73]
	v_mfma_f32_16x16x32_bf16 v[66:69], v[170:173], v[210:213], v[66:69]
	s_setprio 0
	s_barrier
	s_add_i32 s44, s75, s15
	v_lshl_add_u64 v[154:155], v[154:155], 0, s[48:49]
	s_mov_b32 m0, s44
	ds_read_b128 v[174:177], v157 offset:49152
	ds_read_b128 v[178:181], v157 offset:50176
	ds_read_b128 v[182:185], v157 offset:51200
	ds_read_b128 v[186:189], v157 offset:52224
	ds_read_b128 v[190:193], v157 offset:53248
	ds_read_b128 v[202:205], v157 offset:54272
	ds_read_b128 v[206:209], v157 offset:55296
	ds_read_b128 v[210:213], v157 offset:56320
	global_load_lds_dwordx4 v[154:155], off
	s_add_i32 m0, s44, 0x2000
	s_add_u32 s42, s42, 0x40080
	v_lshl_add_u64 v[154:155], v[194:195], 0, s[48:49]
	s_addc_u32 s43, s43, 0
	s_add_i32 s44, s76, s15
	global_load_lds_dwordx4 v[154:155], off
	v_lshl_add_u64 v[154:155], s[42:43], 0, v[130:131]
	s_mov_b32 m0, s44
	s_nop 0
	global_load_lds_dwordx4 v[154:155], off
	v_lshl_add_u64 v[154:155], s[42:43], 0, v[132:133]
	s_add_i32 m0, s44, 0x2000
	s_nop 0
	global_load_lds_dwordx4 v[154:155], off
	v_lshl_add_u64 v[154:155], v[198:199], 0, s[48:49]
	s_mov_b32 m0, s71
	s_nop 0
	global_load_lds_dwordx4 v[154:155], off
	v_lshl_add_u64 v[154:155], v[200:201], 0, s[48:49]
	s_mov_b32 m0, s79
	s_nop 0
	global_load_lds_dwordx4 v[154:155], off
	s_waitcnt vmcnt(8)
	s_waitcnt lgkmcnt(0)
	s_barrier
	s_setprio 1
	s_waitcnt lgkmcnt(0)
	v_mfma_f32_16x16x32_bf16 v[62:65], v[138:141], v[174:177], v[62:65]
	v_mfma_f32_16x16x32_bf16 v[58:61], v[146:149], v[174:177], v[58:61]
	v_mfma_f32_16x16x32_bf16 v[50:53], v[138:141], v[182:185], v[50:53]
	v_mfma_f32_16x16x32_bf16 v[42:45], v[146:149], v[182:185], v[42:45]
	v_mfma_f32_16x16x32_bf16 v[34:37], v[138:141], v[190:193], v[34:37]
	v_mfma_f32_16x16x32_bf16 v[26:29], v[146:149], v[190:193], v[26:29]
	v_mfma_f32_16x16x32_bf16 v[18:21], v[138:141], v[206:209], v[18:21]
	v_mfma_f32_16x16x32_bf16 v[10:13], v[146:149], v[206:209], v[10:13]
	v_mfma_f32_16x16x32_bf16 v[62:65], v[142:145], v[178:181], v[62:65]
	v_mfma_f32_16x16x32_bf16 v[58:61], v[150:153], v[178:181], v[58:61]
	v_mfma_f32_16x16x32_bf16 v[50:53], v[142:145], v[186:189], v[50:53]
	v_mfma_f32_16x16x32_bf16 v[42:45], v[150:153], v[186:189], v[42:45]
	v_mfma_f32_16x16x32_bf16 v[34:37], v[142:145], v[202:205], v[34:37]
	v_mfma_f32_16x16x32_bf16 v[26:29], v[150:153], v[202:205], v[26:29]
	v_mfma_f32_16x16x32_bf16 v[18:21], v[142:145], v[210:213], v[18:21]
	v_mfma_f32_16x16x32_bf16 v[10:13], v[150:153], v[210:213], v[10:13]
	s_setprio 0
	s_setprio 1
	v_mfma_f32_16x16x32_bf16 v[54:57], v[158:161], v[174:177], v[54:57]
	v_mfma_f32_16x16x32_bf16 v[46:49], v[166:169], v[174:177], v[46:49]
	v_mfma_f32_16x16x32_bf16 v[38:41], v[158:161], v[182:185], v[38:41]
	v_mfma_f32_16x16x32_bf16 v[30:33], v[166:169], v[182:185], v[30:33]
	v_mfma_f32_16x16x32_bf16 v[22:25], v[158:161], v[190:193], v[22:25]
	v_mfma_f32_16x16x32_bf16 v[14:17], v[166:169], v[190:193], v[14:17]
	v_mfma_f32_16x16x32_bf16 v[6:9], v[158:161], v[206:209], v[6:9]
	v_mfma_f32_16x16x32_bf16 v[2:5], v[166:169], v[206:209], v[2:5]
	v_mfma_f32_16x16x32_bf16 v[54:57], v[162:165], v[178:181], v[54:57]
	v_mfma_f32_16x16x32_bf16 v[46:49], v[170:173], v[178:181], v[46:49]
	v_mfma_f32_16x16x32_bf16 v[38:41], v[162:165], v[186:189], v[38:41]
	v_mfma_f32_16x16x32_bf16 v[30:33], v[170:173], v[186:189], v[30:33]
	v_mfma_f32_16x16x32_bf16 v[22:25], v[162:165], v[202:205], v[22:25]
	v_mfma_f32_16x16x32_bf16 v[14:17], v[170:173], v[202:205], v[14:17]
	v_mfma_f32_16x16x32_bf16 v[6:9], v[162:165], v[210:213], v[6:9]
	v_mfma_f32_16x16x32_bf16 v[2:5], v[170:173], v[210:213], v[2:5]
	s_setprio 0
	s_barrier
	s_add_i32 vcc_hi, vcc_hi, 2
	s_add_u32 s16, s16, 0x100
	s_addc_u32 s17, s17, 0
	s_add_u32 s74, s74, 0x100
	s_addc_u32 vcc_lo, vcc_lo, 0
	s_cmp_gt_u32 vcc_hi, 13
	s_cbranch_scc0 .LBB0_374
	s_ashr_i32 s16, s78, 31
	s_lshr_b32 s16, s16, 26
	s_add_i32 s16, s78, s16
	s_ashr_i32 s42, s16, 6
	s_andn2_b32 s16, s16, 63
	s_sub_i32 s43, s78, s16
	v_mov_b32 v164, v0
	s_cmpk_gt_i32 s78, 0x17f
	v_ashrrev_i32_e32 v161, 8, v164
	v_bfe_u32 v160, v164, 6, 2
	v_and_b32_e32 v162, 15, v164
	v_lshrrev_b32_e32 v158, 4, v164
	v_bfe_u32 v159, v164, 4, 2
	s_mov_b64 s[16:17], -1
	s_mov_b32 s81, 0x8000
	s_mov_b32 s77, 0x7f807f81
	s_movk_i32 s75, 0x410
	s_movk_i32 s76, 0xfbfc
	s_cbranch_scc0 .LBB0_381
	s_lshl_b32 s16, s43, 8
	s_and_b32 s44, s16, 0x700
	s_cmp_gt_u32 s42, 7
	s_mov_b64 s[16:17], -1
	v_lshl_add_u32 v163, v161, 6, s44
	s_cbranch_scc0 .LBB0_378
	v_bfe_u32 v138, v162, 2, 1
	v_lshrrev_b32_e32 v139, 3, v162
	v_and_b32_e32 v140, 3, v162
	v_lshl_add_u32 v139, v139, 2, v140
	v_lshlrev_b32_e32 v138, 5, v138
	v_lshl_add_u32 v138, v159, 2, v138
	v_lshlrev_b32_e32 v138, 4, v138
	v_lshl_add_u32 v138, v139, 1, v138
	v_lshrrev_b32_e32 v140, 6, v164
	v_lshlrev_b32_e32 v140, 11, v140
	v_add_u32_e32 v140, 0x21010, v140
	v_add_u32_e32 v138, v138, v140
	v_and_b32_e32 v141, 63, v164
	v_lshl_add_u32 v139, v141, 4, v140
	v_lshlrev_b32_e32 v141, 4, v141
	v_readfirstlane_b32 s16, v164
	s_nop 0
	s_lshr_b32 s16, s16, 6
	s_lshr_b32 s17, s16, 2
	s_and_b32 s16, s16, 3
	s_lshr_b32 s44, s43, 3
	s_lshl_b32 s44, s44, 3
	s_add_i32 s45, s42, -8
	s_lshl_b32 s45, s45, 2
	s_add_i32 s44, s44, s45
	s_lshr_b32 s45, s16, 1
	s_add_i32 s44, s44, s45
	s_lshl_b32 s44, s44, 7
	s_and_b32 s45, s43, 7
	s_lshl_b32 s45, s45, 4
	s_add_i32 s44, s44, s45
	s_lshl_b32 s45, s17, 2
	s_add_i32 s44, s44, s45
	s_lshl_b32 s44, s44, 1
	s_and_b32 s45, s16, 1
	s_add_i32 s44, s44, s45
	s_lshl_b32 s44, s44, 10
	v_readlane_b32 s82, v255, 39
	v_readlane_b32 s83, v255, 40
	s_add_u32 s82, s82, s44
	s_addc_u32 s83, s83, 0
	v_cvt_pk_bf16_f32 v150, v126, v127
	v_cvt_pk_bf16_f32 v151, v128, v129
	v_cvt_pk_bf16_f32 v152, v122, v123
	v_cvt_pk_bf16_f32 v153, v124, v125
	ds_write_b16 v138, v150
	ds_write_b16_d16_hi v138, v150 offset:16
	ds_write_b16 v138, v151 offset:32
	ds_write_b16_d16_hi v138, v151 offset:48
	ds_write_b16 v138, v152 offset:256
	ds_write_b16_d16_hi v138, v152 offset:272
	ds_write_b16 v138, v153 offset:288
	ds_write_b16_d16_hi v138, v153 offset:304
	ds_read_b128 v[142:145], v139
	v_cvt_pk_bf16_f32 v166, v114, v115
	v_cvt_pk_bf16_f32 v167, v116, v117
	v_cvt_pk_bf16_f32 v168, v106, v107
	v_cvt_pk_bf16_f32 v169, v108, v109
	ds_write_b16 v138, v166
	ds_write_b16_d16_hi v138, v166 offset:16
	ds_write_b16 v138, v167 offset:32
	ds_write_b16_d16_hi v138, v167 offset:48
	ds_write_b16 v138, v168 offset:256
	ds_write_b16_d16_hi v138, v168 offset:272
	ds_write_b16 v138, v169 offset:288
	ds_write_b16_d16_hi v138, v169 offset:304
	ds_read_b128 v[146:149], v139
	s_waitcnt lgkmcnt(9)
	s_add_u32 s20, s82, 0x0
	s_addc_u32 s21, s83, 0
	global_store_dwordx4 v141, v[142:145], s[20:21]
	v_cvt_pk_bf16_f32 v150, v98, v99
	v_cvt_pk_bf16_f32 v151, v100, v101
	v_cvt_pk_bf16_f32 v152, v90, v91
	v_cvt_pk_bf16_f32 v153, v92, v93
	ds_write_b16 v138, v150
	ds_write_b16_d16_hi v138, v150 offset:16
	ds_write_b16 v138, v151 offset:32
	ds_write_b16_d16_hi v138, v151 offset:48
	ds_write_b16 v138, v152 offset:256
	ds_write_b16_d16_hi v138, v152 offset:272
	ds_write_b16 v138, v153 offset:288
	ds_write_b16_d16_hi v138, v153 offset:304
	ds_read_b128 v[142:145], v139
	s_waitcnt lgkmcnt(9)
	s_add_u32 s20, s82, 0x0
	s_addc_u32 s21, s83, 0
	global_store_dwordx4 v141, v[146:149], s[20:21] offset:2048
	v_cvt_pk_bf16_f32 v166, v82, v83
	v_cvt_pk_bf16_f32 v167, v84, v85
	v_cvt_pk_bf16_f32 v168, v74, v75
	v_cvt_pk_bf16_f32 v169, v76, v77
	ds_write_b16 v138, v166
	ds_write_b16_d16_hi v138, v166 offset:16
	ds_write_b16 v138, v167 offset:32
	ds_write_b16_d16_hi v138, v167 offset:48
	ds_write_b16 v138, v168 offset:256
	ds_write_b16_d16_hi v138, v168 offset:272
	ds_write_b16 v138, v169 offset:288
	ds_write_b16_d16_hi v138, v169 offset:304
	ds_read_b128 v[146:149], v139
	s_waitcnt lgkmcnt(9)
	s_add_u32 s20, s82, 0x1000
	s_addc_u32 s21, s83, 0
	global_store_dwordx4 v141, v[142:145], s[20:21]
	v_cvt_pk_bf16_f32 v150, v62, v63
	v_cvt_pk_bf16_f32 v151, v64, v65
	v_cvt_pk_bf16_f32 v152, v58, v59
	v_cvt_pk_bf16_f32 v153, v60, v61
	ds_write_b16 v138, v150
	ds_write_b16_d16_hi v138, v150 offset:16
	ds_write_b16 v138, v151 offset:32
	ds_write_b16_d16_hi v138, v151 offset:48
	ds_write_b16 v138, v152 offset:256
	ds_write_b16_d16_hi v138, v152 offset:272
	ds_write_b16 v138, v153 offset:288
	ds_write_b16_d16_hi v138, v153 offset:304
	ds_read_b128 v[142:145], v139
	s_waitcnt lgkmcnt(9)
	s_add_u32 s20, s82, 0x1000
	s_addc_u32 s21, s83, 0
	global_store_dwordx4 v141, v[146:149], s[20:21] offset:2048
	v_cvt_pk_bf16_f32 v166, v50, v51
	v_cvt_pk_bf16_f32 v167, v52, v53
	v_cvt_pk_bf16_f32 v168, v42, v43
	v_cvt_pk_bf16_f32 v169, v44, v45
	ds_write_b16 v138, v166
	ds_write_b16_d16_hi v138, v166 offset:16
	ds_write_b16 v138, v167 offset:32
	ds_write_b16_d16_hi v138, v167 offset:48
	ds_write_b16 v138, v168 offset:256
	ds_write_b16_d16_hi v138, v168 offset:272
	ds_write_b16 v138, v169 offset:288
	ds_write_b16_d16_hi v138, v169 offset:304
	ds_read_b128 v[146:149], v139
	s_waitcnt lgkmcnt(9)
	s_add_u32 s20, s82, 0x4000
	s_addc_u32 s21, s83, 0
	global_store_dwordx4 v141, v[142:145], s[20:21]
	v_cvt_pk_bf16_f32 v150, v34, v35
	v_cvt_pk_bf16_f32 v151, v36, v37
	v_cvt_pk_bf16_f32 v152, v26, v27
	v_cvt_pk_bf16_f32 v153, v28, v29
	ds_write_b16 v138, v150
	ds_write_b16_d16_hi v138, v150 offset:16
	ds_write_b16 v138, v151 offset:32
	ds_write_b16_d16_hi v138, v151 offset:48
	ds_write_b16 v138, v152 offset:256
	ds_write_b16_d16_hi v138, v152 offset:272
	ds_write_b16 v138, v153 offset:288
	ds_write_b16_d16_hi v138, v153 offset:304
	ds_read_b128 v[142:145], v139
	s_waitcnt lgkmcnt(9)
	s_add_u32 s20, s82, 0x4000
	s_addc_u32 s21, s83, 0
	global_store_dwordx4 v141, v[146:149], s[20:21] offset:2048
	v_cvt_pk_bf16_f32 v166, v18, v19
	v_cvt_pk_bf16_f32 v167, v20, v21
	v_cvt_pk_bf16_f32 v168, v10, v11
	v_cvt_pk_bf16_f32 v169, v12, v13
	ds_write_b16 v138, v166
	ds_write_b16_d16_hi v138, v166 offset:16
	ds_write_b16 v138, v167 offset:32
	ds_write_b16_d16_hi v138, v167 offset:48
	ds_write_b16 v138, v168 offset:256
	ds_write_b16_d16_hi v138, v168 offset:272
	ds_write_b16 v138, v169 offset:288
	ds_write_b16_d16_hi v138, v169 offset:304
	ds_read_b128 v[146:149], v139
	s_waitcnt lgkmcnt(9)
	s_add_u32 s20, s82, 0x5000
	s_addc_u32 s21, s83, 0
	global_store_dwordx4 v141, v[142:145], s[20:21]
	v_cvt_pk_bf16_f32 v150, v118, v119
	v_cvt_pk_bf16_f32 v151, v120, v121
	v_cvt_pk_bf16_f32 v152, v110, v111
	v_cvt_pk_bf16_f32 v153, v112, v113
	ds_write_b16 v138, v150
	ds_write_b16_d16_hi v138, v150 offset:16
	ds_write_b16 v138, v151 offset:32
	ds_write_b16_d16_hi v138, v151 offset:48
	ds_write_b16 v138, v152 offset:256
	ds_write_b16_d16_hi v138, v152 offset:272
	ds_write_b16 v138, v153 offset:288
	ds_write_b16_d16_hi v138, v153 offset:304
	ds_read_b128 v[142:145], v139
	s_waitcnt lgkmcnt(9)
	s_add_u32 s20, s82, 0x5000
	s_addc_u32 s21, s83, 0
	global_store_dwordx4 v141, v[146:149], s[20:21] offset:2048
	v_cvt_pk_bf16_f32 v166, v102, v103
	v_cvt_pk_bf16_f32 v167, v104, v105
	v_cvt_pk_bf16_f32 v168, v94, v95
	v_cvt_pk_bf16_f32 v169, v96, v97
	ds_write_b16 v138, v166
	ds_write_b16_d16_hi v138, v166 offset:16
	ds_write_b16 v138, v167 offset:32
	ds_write_b16_d16_hi v138, v167 offset:48
	ds_write_b16 v138, v168 offset:256
	ds_write_b16_d16_hi v138, v168 offset:272
	ds_write_b16 v138, v169 offset:288
	ds_write_b16_d16_hi v138, v169 offset:304
	ds_read_b128 v[146:149], v139
	s_waitcnt lgkmcnt(9)
	s_add_u32 s20, s82, 0x80000
	s_addc_u32 s21, s83, 0
	global_store_dwordx4 v141, v[142:145], s[20:21]
	v_cvt_pk_bf16_f32 v150, v86, v87
	v_cvt_pk_bf16_f32 v151, v88, v89
	v_cvt_pk_bf16_f32 v152, v78, v79
	v_cvt_pk_bf16_f32 v153, v80, v81
	ds_write_b16 v138, v150
	ds_write_b16_d16_hi v138, v150 offset:16
	ds_write_b16 v138, v151 offset:32
	ds_write_b16_d16_hi v138, v151 offset:48
	ds_write_b16 v138, v152 offset:256
	ds_write_b16_d16_hi v138, v152 offset:272
	ds_write_b16 v138, v153 offset:288
	ds_write_b16_d16_hi v138, v153 offset:304
	ds_read_b128 v[142:145], v139
	s_waitcnt lgkmcnt(9)
	s_add_u32 s20, s82, 0x80000
	s_addc_u32 s21, s83, 0
	global_store_dwordx4 v141, v[146:149], s[20:21] offset:2048
	v_cvt_pk_bf16_f32 v166, v70, v71
	v_cvt_pk_bf16_f32 v167, v72, v73
	v_cvt_pk_bf16_f32 v168, v66, v67
	v_cvt_pk_bf16_f32 v169, v68, v69
	ds_write_b16 v138, v166
	ds_write_b16_d16_hi v138, v166 offset:16
	ds_write_b16 v138, v167 offset:32
	ds_write_b16_d16_hi v138, v167 offset:48
	ds_write_b16 v138, v168 offset:256
	ds_write_b16_d16_hi v138, v168 offset:272
	ds_write_b16 v138, v169 offset:288
	ds_write_b16_d16_hi v138, v169 offset:304
	ds_read_b128 v[146:149], v139
	s_waitcnt lgkmcnt(9)
	s_add_u32 s20, s82, 0x81000
	s_addc_u32 s21, s83, 0
	global_store_dwordx4 v141, v[142:145], s[20:21]
	v_cvt_pk_bf16_f32 v150, v54, v55
	v_cvt_pk_bf16_f32 v151, v56, v57
	v_cvt_pk_bf16_f32 v152, v46, v47
	v_cvt_pk_bf16_f32 v153, v48, v49
	ds_write_b16 v138, v150
	ds_write_b16_d16_hi v138, v150 offset:16
	ds_write_b16 v138, v151 offset:32
	ds_write_b16_d16_hi v138, v151 offset:48
	ds_write_b16 v138, v152 offset:256
	ds_write_b16_d16_hi v138, v152 offset:272
	ds_write_b16 v138, v153 offset:288
	ds_write_b16_d16_hi v138, v153 offset:304
	ds_read_b128 v[142:145], v139
	s_waitcnt lgkmcnt(9)
	s_add_u32 s20, s82, 0x81000
	s_addc_u32 s21, s83, 0
	global_store_dwordx4 v141, v[146:149], s[20:21] offset:2048
	v_cvt_pk_bf16_f32 v166, v38, v39
	v_cvt_pk_bf16_f32 v167, v40, v41
	v_cvt_pk_bf16_f32 v168, v30, v31
	v_cvt_pk_bf16_f32 v169, v32, v33
	ds_write_b16 v138, v166
	ds_write_b16_d16_hi v138, v166 offset:16
	ds_write_b16 v138, v167 offset:32
	ds_write_b16_d16_hi v138, v167 offset:48
	ds_write_b16 v138, v168 offset:256
	ds_write_b16_d16_hi v138, v168 offset:272
	ds_write_b16 v138, v169 offset:288
	ds_write_b16_d16_hi v138, v169 offset:304
	ds_read_b128 v[146:149], v139
	s_waitcnt lgkmcnt(9)
	s_add_u32 s20, s82, 0x84000
	s_addc_u32 s21, s83, 0
	global_store_dwordx4 v141, v[142:145], s[20:21]
	v_cvt_pk_bf16_f32 v150, v22, v23
	v_cvt_pk_bf16_f32 v151, v24, v25
	v_cvt_pk_bf16_f32 v152, v14, v15
	v_cvt_pk_bf16_f32 v153, v16, v17
	ds_write_b16 v138, v150
	ds_write_b16_d16_hi v138, v150 offset:16
	ds_write_b16 v138, v151 offset:32
	ds_write_b16_d16_hi v138, v151 offset:48
	ds_write_b16 v138, v152 offset:256
	ds_write_b16_d16_hi v138, v152 offset:272
	ds_write_b16 v138, v153 offset:288
	ds_write_b16_d16_hi v138, v153 offset:304
	ds_read_b128 v[142:145], v139
	s_waitcnt lgkmcnt(9)
	s_add_u32 s20, s82, 0x84000
	s_addc_u32 s21, s83, 0
	global_store_dwordx4 v141, v[146:149], s[20:21] offset:2048
	v_cvt_pk_bf16_f32 v166, v6, v7
	v_cvt_pk_bf16_f32 v167, v8, v9
	v_cvt_pk_bf16_f32 v168, v2, v3
	v_cvt_pk_bf16_f32 v169, v4, v5
	ds_write_b16 v138, v166
	ds_write_b16_d16_hi v138, v166 offset:16
	ds_write_b16 v138, v167 offset:32
	ds_write_b16_d16_hi v138, v167 offset:48
	ds_write_b16 v138, v168 offset:256
	ds_write_b16_d16_hi v138, v168 offset:272
	ds_write_b16 v138, v169 offset:288
	ds_write_b16_d16_hi v138, v169 offset:304
	ds_read_b128 v[146:149], v139
	s_waitcnt lgkmcnt(9)
	s_add_u32 s20, s82, 0x85000
	s_addc_u32 s21, s83, 0
	global_store_dwordx4 v141, v[142:145], s[20:21]
	s_waitcnt lgkmcnt(0)
	s_add_u32 s20, s82, 0x85000
	s_addc_u32 s21, s83, 0
	global_store_dwordx4 v141, v[146:149], s[20:21] offset:2048
	s_mov_b64 s[20:21], 0x1fc0080
	s_mov_b64 s[16:17], 0

	.amdhsa_kernel _Z14fwd_megakernel6Params
		.amdhsa_group_segment_fixed_size 16384
		.amdhsa_private_segment_fixed_size 0
		.amdhsa_kernarg_size 448
		.amdhsa_user_sgpr_count 2
		.amdhsa_user_sgpr_dispatch_ptr 0
		.amdhsa_user_sgpr_queue_ptr 0
		.amdhsa_user_sgpr_kernarg_segment_ptr 1
		.amdhsa_user_sgpr_dispatch_id 0
		.amdhsa_user_sgpr_kernarg_preload_length 0
		.amdhsa_user_sgpr_kernarg_preload_offset 0
		.amdhsa_user_sgpr_private_segment_size 0
		.amdhsa_uses_dynamic_stack 0
		.amdhsa_enable_private_segment 0
		.amdhsa_system_sgpr_workgroup_id_x 1
		.amdhsa_system_sgpr_workgroup_id_y 0
		.amdhsa_system_sgpr_workgroup_id_z 0
		.amdhsa_system_sgpr_workgroup_info 0
		.amdhsa_system_vgpr_workitem_id 0
		.amdhsa_next_free_vgpr 256
		.amdhsa_next_free_sgpr 100
		.amdhsa_accum_offset 256
		.amdhsa_reserve_vcc 1
		.amdhsa_float_round_mode_32 0
		.amdhsa_float_round_mode_16_64 0
		.amdhsa_float_denorm_mode_32 3
		.amdhsa_float_denorm_mode_16_64 3
		.amdhsa_dx10_clamp 1
		.amdhsa_ieee_mode 1
		.amdhsa_fp16_overflow 0
		.amdhsa_tg_split 0
		.amdhsa_exception_fp_ieee_invalid_op 0
		.amdhsa_exception_fp_denorm_src 0
		.amdhsa_exception_fp_ieee_div_zero 0
		.amdhsa_exception_fp_ieee_overflow 0
		.amdhsa_exception_fp_ieee_underflow 0
		.amdhsa_exception_fp_ieee_inexact 0
		.amdhsa_exception_int_div_zero 0
	.end_amdhsa_kernel

amdhsa.kernels:
  - .agpr_count:     0
    .args:
      - .offset:         0
        .size:           192
        .value_kind:     by_value
      - .offset:         192
        .size:           4
        .value_kind:     hidden_block_count_x
      - .offset:         196
        .size:           4
        .value_kind:     hidden_block_count_y
      - .offset:         200
        .size:           4
        .value_kind:     hidden_block_count_z
      - .offset:         204
        .size:           2
        .value_kind:     hidden_group_size_x
      - .offset:         206
        .size:           2
        .value_kind:     hidden_group_size_y
      - .offset:         208
        .size:           2
        .value_kind:     hidden_group_size_z
      - .offset:         210
        .size:           2
        .value_kind:     hidden_remainder_x
      - .offset:         212
        .size:           2
        .value_kind:     hidden_remainder_y
      - .offset:         214
        .size:           2
        .value_kind:     hidden_remainder_z
      - .offset:         232
        .size:           8
        .value_kind:     hidden_global_offset_x
      - .offset:         240
        .size:           8
        .value_kind:     hidden_global_offset_y
      - .offset:         248
        .size:           8
        .value_kind:     hidden_global_offset_z
      - .offset:         256
        .size:           2
        .value_kind:     hidden_grid_dims
      - .offset:         312
        .size:           4
        .value_kind:     hidden_dynamic_lds_size
    .group_segment_fixed_size: 16384
    .kernarg_segment_align: 8
    .kernarg_segment_size: 448
    .language:       OpenCL C
    .language_version:
      - 2
      - 0
    .max_flat_workgroup_size: 512
    .name:           _Z14fwd_megakernel6Params
    .private_segment_fixed_size: 0
    .sgpr_count:     106
    .sgpr_spill_count: 183
    .symbol:         _Z14fwd_megakernel6Params.kd
    .uniform_work_group_size: 1
    .uses_dynamic_stack: false
    .vgpr_count:     256
    .vgpr_spill_count: 0
    .wavefront_size: 64
